# FF1 GEMMs: first two vmcnt waits of a tile relaxed to 8+8 so epilogue stores drain behind the first K-tile
# baseline (speedup 1.0000x reference)
; #define PG8_STAGE(bufoff, gbase, voff) do { _Pragma("unroll") for (int _i = 0; _i < 2; ++_i) \
;         __builtin_amdgcn_global_load_lds((const unsigned*)((const char*)(gbase) + (voff)[_i]), (PG8_LAS unsigned*)(lds + (bufoff) + ldsw + _i * 8192), 16, 0, 0); } while (0)
; #define PG8_LDA(dst, b, h) do { _Pragma("unroll") for (int m = 0; m < 4; ++m) _Pragma("unroll") for (int k = 0; k < 2; ++k) dst[m][k] = *(const PG8_LAS bf16x8*)(lds + PG8_SA(b, h) + aoff + m * 2048 + k * 1024); } while (0)
; #define PG8_LDB(dst, b, h) do { _Pragma("unroll") for (int n = 0; n < 2; ++n) _Pragma("unroll") for (int k = 0; k < 2; ++k) dst[n][k] = *(const PG8_LAS bf16x8*)(lds + PG8_SB(b, h) + boff + n * 2048 + k * 1024); } while (0)
; #define PG8_SCHED __builtin_amdgcn_sched_barrier(0)
; template <class Epi, class Sched, bool ALIGN_EPI = false, bool SP2 = false>
; __device__ __forceinline__ void gemm_phase(PG8_LAS unsigned char* lds, const Gemm g, const Sched& S, const Epi& E) {
;     ...
;     for (;;) {
;         const bool has_next = S.next(ui + 1, nxt);
;         const char* nA = has_next ? (const char*)g.A + (size_t)nxt.pm * tstep : cA; const char* nB = has_next ? (const char*)g.Bt + (size_t)nxt.pn * tstep : cB;
;         for (int t = 0; t < nt; t += 2) {
;             const bool last = (t == nt - 2);
;             const char* a1 = cA + (size_t)(t + 1) * kstep;
;             const char* a2 = last ? nA : cA + (size_t)(t + 2) * kstep; const char* b2 = last ? nB : cB + (size_t)(t + 2) * kstep;
;             const char* a3 = a2 + kstep; const char* b3 = b2 + kstep;
;             if (last && has_next) S.a_ready(nxt);
;             if constexpr (SP2) {
;             PG8_LDB(B0, 0, 0); PG8_LDB(B1, 0, 1); PG8_SCHED; PG8_LDA(At, 0, 0); PG8_STAGE(PG8_SA(1, 1), a1 + hstep, voffA);
;     ...
;         for (int a = 0; a < 2; ++a)
; #pragma unroll
;             for (int b = 0; b < 2; ++b)
; #pragma unroll
;                 for (int m = 0; m < 4; ++m)
; #pragma unroll
;                     for (int n = 0; n < 2; ++n) acc[a][b][m][n] = (f32x4){0.f, 0.f, 0.f, 0.f};
.LBB0_713:
	s_ashr_i32 s23, s22, 31
	s_lshl_b64 s[24:25], s[22:23], 19
	s_add_u32 s24, s16, s24
	s_addc_u32 s25, s17, s25
	s_and_b64 s[36:37], s[0:1], exec
	s_cselect_b32 s23, s25, s41
	s_cselect_b32 s72, s24, s40
	s_ashr_i32 s21, s20, 31
	s_lshl_b64 s[36:37], s[20:21], 19
	s_add_u32 s36, s46, s36
	s_addc_u32 s37, s47, s37
	s_and_b64 s[44:45], s[0:1], exec
	s_cselect_b32 s21, s37, s43
	s_cselect_b32 s73, s36, s42
	s_add_u32 s40, s40, 0x40080
	s_addc_u32 s41, s41, 0
	s_add_u32 s74, s42, 0x100
	v_mov_b32_e32 v0, 0
	s_addc_u32 s75, s43, 0
	s_mov_b32 s76, -2
	s_cmp_gt_u32 s58, 1
	s_cselect_b32 s32, 1, 0
	v_mov_b32_e32 v1, v0
	v_mov_b32_e32 v2, v0
	v_mov_b32_e32 v3, v0
	v_mov_b32_e32 v8, v0
	v_mov_b32_e32 v9, v0
	v_mov_b32_e32 v10, v0
	v_mov_b32_e32 v11, v0
	v_mov_b32_e32 v16, v0
	v_mov_b32_e32 v17, v0
	v_mov_b32_e32 v18, v0
	v_mov_b32_e32 v19, v0
	v_mov_b32_e32 v24, v0
	v_mov_b32_e32 v25, v0
	v_mov_b32_e32 v26, v0
	v_mov_b32_e32 v27, v0
	v_mov_b32_e32 v32, v0
	v_mov_b32_e32 v33, v0
	v_mov_b32_e32 v34, v0
	v_mov_b32_e32 v35, v0
	v_mov_b32_e32 v40, v0
	v_mov_b32_e32 v41, v0
	v_mov_b32_e32 v42, v0
	v_mov_b32_e32 v43, v0
	v_mov_b32_e32 v48, v0
	v_mov_b32_e32 v49, v0
	v_mov_b32_e32 v50, v0
	v_mov_b32_e32 v51, v0
	v_mov_b32_e32 v56, v0
	v_mov_b32_e32 v57, v0
	v_mov_b32_e32 v58, v0
	v_mov_b32_e32 v59, v0
	v_mov_b32_e32 v4, v0
	v_mov_b32_e32 v5, v0
	v_mov_b32_e32 v6, v0
	v_mov_b32_e32 v7, v0
	v_mov_b32_e32 v12, v0
	v_mov_b32_e32 v13, v0
	v_mov_b32_e32 v14, v0
	v_mov_b32_e32 v15, v0
	v_mov_b32_e32 v20, v0
	v_mov_b32_e32 v21, v0
	s_waitcnt lgkmcnt(0)
	v_mov_b32_e32 v22, v0
	v_mov_b32_e32 v23, v0
	v_mov_b32_e32 v28, v0
	v_mov_b32_e32 v29, v0
	v_mov_b32_e32 v30, v0
	v_mov_b32_e32 v31, v0
	v_mov_b32_e32 v36, v0
	v_mov_b32_e32 v37, v0
	v_mov_b32_e32 v38, v0
	v_mov_b32_e32 v39, v0
	v_mov_b32_e32 v44, v0
	v_mov_b32_e32 v45, v0
	v_mov_b32_e32 v46, v0
	v_mov_b32_e32 v47, v0
	v_mov_b32_e32 v52, v0
	v_mov_b32_e32 v53, v0
	v_mov_b32_e32 v54, v0
	v_mov_b32_e32 v55, v0
	v_mov_b32_e32 v60, v0
	v_mov_b32_e32 v61, v0
	v_mov_b32_e32 v62, v0
	v_mov_b32_e32 v63, v0
	v_mov_b32_e32 v64, v0
	v_mov_b32_e32 v65, v0
	v_mov_b32_e32 v66, v0
	v_mov_b32_e32 v67, v0
	v_mov_b32_e32 v72, v0
	v_mov_b32_e32 v73, v0
	v_mov_b32_e32 v74, v0
	v_mov_b32_e32 v75, v0
	v_mov_b32_e32 v80, v0
	v_mov_b32_e32 v81, v0
	v_mov_b32_e32 v82, v0
	v_mov_b32_e32 v83, v0
	v_mov_b32_e32 v88, v0
	v_mov_b32_e32 v89, v0
	v_mov_b32_e32 v90, v0
	v_mov_b32_e32 v91, v0
	v_mov_b32_e32 v96, v0
	v_mov_b32_e32 v97, v0
	v_mov_b32_e32 v98, v0
	v_mov_b32_e32 v99, v0
	v_mov_b32_e32 v104, v0
	v_mov_b32_e32 v105, v0
	v_mov_b32_e32 v106, v0
	v_mov_b32_e32 v107, v0
	v_mov_b32_e32 v112, v0
	v_mov_b32_e32 v113, v0
	v_mov_b32_e32 v114, v0
	v_mov_b32_e32 v115, v0
	v_mov_b32_e32 v120, v0
	v_mov_b32_e32 v121, v0
	v_mov_b32_e32 v122, v0
	v_mov_b32_e32 v123, v0
	v_mov_b32_e32 v68, v0
	v_mov_b32_e32 v69, v0
	v_mov_b32_e32 v70, v0
	v_mov_b32_e32 v71, v0
	v_mov_b32_e32 v76, v0
	v_mov_b32_e32 v77, v0
	v_mov_b32_e32 v78, v0
	v_mov_b32_e32 v79, v0
	v_mov_b32_e32 v84, v0
	v_mov_b32_e32 v85, v0
	v_mov_b32_e32 v86, v0
	v_mov_b32_e32 v87, v0
	v_mov_b32_e32 v92, v0
	v_mov_b32_e32 v93, v0
	v_mov_b32_e32 v94, v0
	v_mov_b32_e32 v95, v0
	v_mov_b32_e32 v100, v0
	v_mov_b32_e32 v101, v0
	v_mov_b32_e32 v102, v0
	v_mov_b32_e32 v103, v0
	v_mov_b32_e32 v108, v0
	v_mov_b32_e32 v109, v0
	v_mov_b32_e32 v110, v0
	v_mov_b32_e32 v111, v0
	v_mov_b32_e32 v116, v0
	v_mov_b32_e32 v117, v0
	v_mov_b32_e32 v118, v0
	v_mov_b32_e32 v119, v0
	v_mov_b32_e32 v124, v0
	v_mov_b32_e32 v125, v0
	v_mov_b32_e32 v126, v0
	v_mov_b32_e32 v127, v0
.LBB0_714:
	ds_read_b128 v[154:157], v147
	ds_read_b128 v[158:161], v147 offset:1024
	ds_read_b128 v[162:165], v147 offset:2048
	ds_read_b128 v[166:169], v147 offset:3072
	ds_read_b128 v[170:173], v148
	ds_read_b128 v[174:177], v148 offset:1024
	ds_read_b128 v[178:181], v148 offset:2048
	ds_read_b128 v[182:185], v148 offset:3072
	s_add_u32 s33, s40, 0xfffc0080
	s_addc_u32 s34, s41, -1
	s_cmp_eq_u32 s76, 12
	s_cselect_b32 s45, s23, s34
	s_cselect_b32 s44, s72, s33
	s_cselect_b32 s43, s21, s75
	s_cselect_b32 s42, s73, s74
	v_lshl_add_u64 v[150:151], s[40:41], 0, v[136:137]
	s_add_i32 m0, s39, 0xc000
	ds_read_b128 v[186:189], v149
	ds_read_b128 v[190:193], v149 offset:1024
	ds_read_b128 v[194:197], v149 offset:2048
	ds_read_b128 v[198:201], v149 offset:3072
	ds_read_b128 v[202:205], v149 offset:4096
	ds_read_b128 v[206:209], v149 offset:5120
	ds_read_b128 v[210:213], v149 offset:6144
	ds_read_b128 v[214:217], v149 offset:7168
	global_load_lds_dwordx4 v[150:151], off
	v_lshl_add_u64 v[150:151], s[40:41], 0, v[138:139]
	s_add_i32 m0, s39, 0xe000
	s_nop 0
	global_load_lds_dwordx4 v[150:151], off
	s_cmp_eq_u32 s32, 0
	s_cbranch_scc1 .Lrw8_p7_0
	s_waitcnt vmcnt(16)
	s_branch .Lrwd_p7_0
; #define PG8_STAGE(bufoff, gbase, voff) do { _Pragma("unroll") for (int _i = 0; _i < 2; ++_i) \
;         __builtin_amdgcn_global_load_lds((const unsigned*)((const char*)(gbase) + (voff)[_i]), (PG8_LAS unsigned*)(lds + (bufoff) + ldsw + _i * 8192), 16, 0, 0); } while (0)
; #define PG8_LDA(dst, b, h) do { _Pragma("unroll") for (int m = 0; m < 4; ++m) _Pragma("unroll") for (int k = 0; k < 2; ++k) dst[m][k] = *(const PG8_LAS bf16x8*)(lds + PG8_SA(b, h) + aoff + m * 2048 + k * 1024); } while (0)
; #define PG8_LDB(dst, b, h) do { _Pragma("unroll") for (int n = 0; n < 2; ++n) _Pragma("unroll") for (int k = 0; k < 2; ++k) dst[n][k] = *(const PG8_LAS bf16x8*)(lds + PG8_SB(b, h) + boff + n * 2048 + k * 1024); } while (0)
; #define PG8_MMA(ai, bj, At, Bt) do { __builtin_amdgcn_s_setprio(1); _Pragma("unroll") for (int m = 0; m < 4; ++m) _Pragma("unroll") for (int n = 0; n < 2; ++n) _Pragma("unroll") for (int k = 0; k < 2; ++k) \
;         acc[ai][bj][m][n] = __builtin_amdgcn_mfma_f32_16x16x32_bf16(Bt[n][k], At[m][k], acc[ai][bj][m][n], 0, 0, 0); __builtin_amdgcn_s_setprio(0); } while (0)
; #define PG8_WAIT_V(n) asm volatile("s_waitcnt vmcnt(" #n ")" ::: "memory")
; #define PG8_WAIT_L(n) asm volatile("s_waitcnt lgkmcnt(" #n ")" ::: "memory")
; #define PG8_BAR __builtin_amdgcn_s_barrier()
; #define PG8_SCHED __builtin_amdgcn_sched_barrier(0)
; template <class Epi, class Sched, bool ALIGN_EPI = false, bool SP2 = false>
; __device__ __forceinline__ void gemm_phase(PG8_LAS unsigned char* lds, const Gemm g, const Sched& S, const Epi& E) {
;     ...
;             PG8_LDB(B0, 0, 0); PG8_LDB(B1, 0, 1); PG8_SCHED; PG8_LDA(At, 0, 0); PG8_STAGE(PG8_SA(1, 1), a1 + hstep, voffA);
;             PG8_WAIT_V(8); PG8_WAIT_L(0); PG8_BAR; PG8_MMA(0, 0, At, B0); PG8_MMA(0, 1, At, B1); PG8_BAR; PG8_SCHED;
;             PG8_LDA(At, 0, 1); PG8_STAGE(PG8_SB(0, 0), b2, voffB); PG8_STAGE(PG8_SB(0, 1), b2 + hstep, voffB); PG8_STAGE(PG8_SA(0, 0), a2, voffA);
.Lrw8_p7_0:
	s_waitcnt vmcnt(8)
.Lrwd_p7_0:
	s_waitcnt lgkmcnt(0)
	s_barrier
	s_setprio 1
	s_waitcnt lgkmcnt(0)
	v_mfma_f32_16x16x32_bf16 v[124:127], v[154:157], v[186:189], v[124:127]
	v_mfma_f32_16x16x32_bf16 v[116:119], v[162:165], v[186:189], v[116:119]
	v_mfma_f32_16x16x32_bf16 v[108:111], v[154:157], v[194:197], v[108:111]
	v_mfma_f32_16x16x32_bf16 v[100:103], v[162:165], v[194:197], v[100:103]
	v_mfma_f32_16x16x32_bf16 v[92:95], v[154:157], v[202:205], v[92:95]
	v_mfma_f32_16x16x32_bf16 v[84:87], v[162:165], v[202:205], v[84:87]
	v_mfma_f32_16x16x32_bf16 v[76:79], v[154:157], v[210:213], v[76:79]
	v_mfma_f32_16x16x32_bf16 v[68:71], v[162:165], v[210:213], v[68:71]
	v_mfma_f32_16x16x32_bf16 v[124:127], v[158:161], v[190:193], v[124:127]
	v_mfma_f32_16x16x32_bf16 v[116:119], v[166:169], v[190:193], v[116:119]
	v_mfma_f32_16x16x32_bf16 v[108:111], v[158:161], v[198:201], v[108:111]
	v_mfma_f32_16x16x32_bf16 v[100:103], v[166:169], v[198:201], v[100:103]
	v_mfma_f32_16x16x32_bf16 v[92:95], v[158:161], v[206:209], v[92:95]
	v_mfma_f32_16x16x32_bf16 v[84:87], v[166:169], v[206:209], v[84:87]
	v_mfma_f32_16x16x32_bf16 v[76:79], v[158:161], v[214:217], v[76:79]
	v_mfma_f32_16x16x32_bf16 v[68:71], v[166:169], v[214:217], v[68:71]
	s_setprio 0
	s_setprio 1
	v_mfma_f32_16x16x32_bf16 v[120:123], v[170:173], v[186:189], v[120:123]
	v_mfma_f32_16x16x32_bf16 v[112:115], v[178:181], v[186:189], v[112:115]
	v_mfma_f32_16x16x32_bf16 v[104:107], v[170:173], v[194:197], v[104:107]
	v_mfma_f32_16x16x32_bf16 v[96:99], v[178:181], v[194:197], v[96:99]
	v_mfma_f32_16x16x32_bf16 v[88:91], v[170:173], v[202:205], v[88:91]
	v_mfma_f32_16x16x32_bf16 v[80:83], v[178:181], v[202:205], v[80:83]
	v_mfma_f32_16x16x32_bf16 v[72:75], v[170:173], v[210:213], v[72:75]
	v_mfma_f32_16x16x32_bf16 v[64:67], v[178:181], v[210:213], v[64:67]
	v_mfma_f32_16x16x32_bf16 v[120:123], v[174:177], v[190:193], v[120:123]
	v_mfma_f32_16x16x32_bf16 v[112:115], v[182:185], v[190:193], v[112:115]
	v_mfma_f32_16x16x32_bf16 v[104:107], v[174:177], v[198:201], v[104:107]
	v_mfma_f32_16x16x32_bf16 v[96:99], v[182:185], v[198:201], v[96:99]
	v_mfma_f32_16x16x32_bf16 v[88:91], v[174:177], v[206:209], v[88:91]
	v_mfma_f32_16x16x32_bf16 v[80:83], v[182:185], v[206:209], v[80:83]
	v_mfma_f32_16x16x32_bf16 v[72:75], v[174:177], v[214:217], v[72:75]
	v_mfma_f32_16x16x32_bf16 v[64:67], v[182:185], v[214:217], v[64:67]
	s_setprio 0
	s_barrier
	s_add_i32 s33, s62, s52
	v_lshl_add_u64 v[150:151], s[42:43], 0, v[130:131]
	s_mov_b32 m0, s33
	ds_read_b128 v[186:189], v149 offset:16384
	ds_read_b128 v[190:193], v149 offset:17408
	ds_read_b128 v[194:197], v149 offset:18432
	ds_read_b128 v[198:201], v149 offset:19456
	ds_read_b128 v[202:205], v149 offset:20480
	ds_read_b128 v[206:209], v149 offset:21504
	ds_read_b128 v[210:213], v149 offset:22528
	ds_read_b128 v[214:217], v149 offset:23552
	global_load_lds_dwordx4 v[150:151], off
	s_add_i32 m0, s33, 0x2000
	s_add_u32 s78, s42, 0x40000
	v_lshl_add_u64 v[218:219], s[42:43], 0, v[134:135]
	s_addc_u32 s79, s43, 0
	s_add_i32 s33, s63, s52
	global_load_lds_dwordx4 v[218:219], off
	v_lshl_add_u64 v[220:221], s[78:79], 0, v[130:131]
	s_mov_b32 m0, s33
	v_lshl_add_u64 v[222:223], s[44:45], 0, v[132:133]
	global_load_lds_dwordx4 v[220:221], off
	v_lshl_add_u64 v[220:221], s[78:79], 0, v[134:135]
	s_add_i32 m0, s33, 0x2000
	s_nop 0
	global_load_lds_dwordx4 v[220:221], off
	v_lshl_add_u64 v[220:221], s[44:45], 0, v[128:129]
	s_mov_b32 m0, s39
	s_nop 0
	global_load_lds_dwordx4 v[220:221], off
	s_mov_b32 m0, s55
	s_nop 0
	global_load_lds_dwordx4 v[222:223], off
	s_cmp_eq_u32 s32, 0
	s_cbranch_scc1 .Lrw8_p7_1
	s_waitcnt vmcnt(16)
	s_branch .Lrwd_p7_1

; #define PG8_STAGE(bufoff, gbase, voff) do { _Pragma("unroll") for (int _i = 0; _i < 2; ++_i) \
;         __builtin_amdgcn_global_load_lds((const unsigned*)((const char*)(gbase) + (voff)[_i]), (PG8_LAS unsigned*)(lds + (bufoff) + ldsw + _i * 8192), 16, 0, 0); } while (0)
; #define PG8_LDA(dst, b, h) do { _Pragma("unroll") for (int m = 0; m < 4; ++m) _Pragma("unroll") for (int k = 0; k < 2; ++k) dst[m][k] = *(const PG8_LAS bf16x8*)(lds + PG8_SA(b, h) + aoff + m * 2048 + k * 1024); } while (0)
; #define PG8_LDB(dst, b, h) do { _Pragma("unroll") for (int n = 0; n < 2; ++n) _Pragma("unroll") for (int k = 0; k < 2; ++k) dst[n][k] = *(const PG8_LAS bf16x8*)(lds + PG8_SB(b, h) + boff + n * 2048 + k * 1024); } while (0)
; #define PG8_MMA(ai, bj, At, Bt) do { __builtin_amdgcn_s_setprio(1); _Pragma("unroll") for (int m = 0; m < 4; ++m) _Pragma("unroll") for (int n = 0; n < 2; ++n) _Pragma("unroll") for (int k = 0; k < 2; ++k) \
;         acc[ai][bj][m][n] = __builtin_amdgcn_mfma_f32_16x16x32_bf16(Bt[n][k], At[m][k], acc[ai][bj][m][n], 0, 0, 0); __builtin_amdgcn_s_setprio(0); } while (0)
; #define PG8_WAIT_V(n) asm volatile("s_waitcnt vmcnt(" #n ")" ::: "memory")
; #define PG8_WAIT_L(n) asm volatile("s_waitcnt lgkmcnt(" #n ")" ::: "memory")
; #define PG8_BAR __builtin_amdgcn_s_barrier()
; #define PG8_SCHED __builtin_amdgcn_sched_barrier(0)
; template <class Epi, class Sched, bool ALIGN_EPI = false, bool SP2 = false>
; __device__ __forceinline__ void gemm_phase(PG8_LAS unsigned char* lds, const Gemm g, const Sched& S, const Epi& E) {
;     ...
;             PG8_WAIT_V(8); PG8_WAIT_L(0); PG8_BAR; PG8_MMA(1, 0, At, B0); PG8_MMA(1, 1, At, B1); PG8_BAR; PG8_SCHED;
;             PG8_LDB(B0, 1, 0); PG8_LDB(B1, 1, 1); PG8_SCHED; PG8_LDA(At, 1, 0); PG8_STAGE(PG8_SA(0, 1), a2 + hstep, voffA);
;             PG8_WAIT_V(8); PG8_WAIT_L(0); PG8_BAR; PG8_MMA(0, 0, At, B0); PG8_MMA(0, 1, At, B1); PG8_BAR; PG8_SCHED;
.Lrwd_p7_1:
	s_waitcnt lgkmcnt(0)
	s_barrier
	s_setprio 1
	s_waitcnt lgkmcnt(0)
	v_mfma_f32_16x16x32_bf16 v[60:63], v[154:157], v[186:189], v[60:63]
	v_mfma_f32_16x16x32_bf16 v[52:55], v[162:165], v[186:189], v[52:55]
	v_mfma_f32_16x16x32_bf16 v[44:47], v[154:157], v[194:197], v[44:47]
	v_mfma_f32_16x16x32_bf16 v[36:39], v[162:165], v[194:197], v[36:39]
	v_mfma_f32_16x16x32_bf16 v[28:31], v[154:157], v[202:205], v[28:31]
	v_mfma_f32_16x16x32_bf16 v[20:23], v[162:165], v[202:205], v[20:23]
	v_mfma_f32_16x16x32_bf16 v[12:15], v[154:157], v[210:213], v[12:15]
	v_mfma_f32_16x16x32_bf16 v[4:7], v[162:165], v[210:213], v[4:7]
	v_mfma_f32_16x16x32_bf16 v[60:63], v[158:161], v[190:193], v[60:63]
	v_mfma_f32_16x16x32_bf16 v[52:55], v[166:169], v[190:193], v[52:55]
	v_mfma_f32_16x16x32_bf16 v[44:47], v[158:161], v[198:201], v[44:47]
	v_mfma_f32_16x16x32_bf16 v[36:39], v[166:169], v[198:201], v[36:39]
	v_mfma_f32_16x16x32_bf16 v[28:31], v[158:161], v[206:209], v[28:31]
	v_mfma_f32_16x16x32_bf16 v[20:23], v[166:169], v[206:209], v[20:23]
	v_mfma_f32_16x16x32_bf16 v[12:15], v[158:161], v[214:217], v[12:15]
	v_mfma_f32_16x16x32_bf16 v[4:7], v[166:169], v[214:217], v[4:7]
	s_setprio 0
	s_setprio 1
	v_mfma_f32_16x16x32_bf16 v[56:59], v[170:173], v[186:189], v[56:59]
	v_mfma_f32_16x16x32_bf16 v[48:51], v[178:181], v[186:189], v[48:51]
	v_mfma_f32_16x16x32_bf16 v[40:43], v[170:173], v[194:197], v[40:43]
	v_mfma_f32_16x16x32_bf16 v[32:35], v[178:181], v[194:197], v[32:35]
	v_mfma_f32_16x16x32_bf16 v[24:27], v[170:173], v[202:205], v[24:27]
	v_mfma_f32_16x16x32_bf16 v[16:19], v[178:181], v[202:205], v[16:19]
	v_mfma_f32_16x16x32_bf16 v[8:11], v[170:173], v[210:213], v[8:11]
	v_mfma_f32_16x16x32_bf16 v[0:3], v[178:181], v[210:213], v[0:3]
	v_mfma_f32_16x16x32_bf16 v[56:59], v[174:177], v[190:193], v[56:59]
	v_mfma_f32_16x16x32_bf16 v[48:51], v[182:185], v[190:193], v[48:51]
	v_mfma_f32_16x16x32_bf16 v[40:43], v[174:177], v[198:201], v[40:43]
	v_mfma_f32_16x16x32_bf16 v[32:35], v[182:185], v[198:201], v[32:35]
	v_mfma_f32_16x16x32_bf16 v[24:27], v[174:177], v[206:209], v[24:27]
	v_mfma_f32_16x16x32_bf16 v[16:19], v[182:185], v[206:209], v[16:19]
	v_mfma_f32_16x16x32_bf16 v[8:11], v[174:177], v[214:217], v[8:11]
	v_mfma_f32_16x16x32_bf16 v[0:3], v[182:185], v[214:217], v[0:3]
	s_setprio 0
	s_barrier
	s_add_i32 s33, 0, 0x18000
	v_add_u32_e32 v153, s33, v145
	s_add_i32 s34, 0, 0x1c000
	ds_read_b128 v[154:157], v153
	ds_read_b128 v[158:161], v153 offset:1024
	ds_read_b128 v[162:165], v153 offset:2048
	ds_read_b128 v[166:169], v153 offset:3072
	v_add_u32_e32 v153, s34, v145
	ds_read_b128 v[170:173], v153
	ds_read_b128 v[174:177], v153 offset:1024
	ds_read_b128 v[178:181], v153 offset:2048
	ds_read_b128 v[182:185], v153 offset:3072
	s_add_u32 s44, s44, 0x40000
	s_addc_u32 s45, s45, 0
	s_mov_b32 m0, s56
	v_lshl_add_u64 v[224:225], s[44:45], 0, v[128:129]
	ds_read_b128 v[186:189], v149 offset:32768
	ds_read_b128 v[190:193], v149 offset:33792
	ds_read_b128 v[194:197], v149 offset:34816
	ds_read_b128 v[198:201], v149 offset:35840
	ds_read_b128 v[202:205], v149 offset:36864
	ds_read_b128 v[206:209], v149 offset:37888
	ds_read_b128 v[210:213], v149 offset:38912
	ds_read_b128 v[214:217], v149 offset:39936
	global_load_lds_dwordx4 v[224:225], off
	v_lshl_add_u64 v[224:225], s[44:45], 0, v[132:133]
	s_mov_b32 m0, s57
	s_nop 0
	global_load_lds_dwordx4 v[224:225], off
	s_waitcnt vmcnt(8)
	s_waitcnt lgkmcnt(0)
	s_barrier
	s_setprio 1
	s_waitcnt lgkmcnt(0)
	v_mfma_f32_16x16x32_bf16 v[124:127], v[154:157], v[186:189], v[124:127]
	v_mfma_f32_16x16x32_bf16 v[116:119], v[162:165], v[186:189], v[116:119]
	v_mfma_f32_16x16x32_bf16 v[108:111], v[154:157], v[194:197], v[108:111]
	v_mfma_f32_16x16x32_bf16 v[100:103], v[162:165], v[194:197], v[100:103]
	v_mfma_f32_16x16x32_bf16 v[92:95], v[154:157], v[202:205], v[92:95]
	v_mfma_f32_16x16x32_bf16 v[84:87], v[162:165], v[202:205], v[84:87]
	v_mfma_f32_16x16x32_bf16 v[76:79], v[154:157], v[210:213], v[76:79]
	v_mfma_f32_16x16x32_bf16 v[68:71], v[162:165], v[210:213], v[68:71]
	v_mfma_f32_16x16x32_bf16 v[124:127], v[158:161], v[190:193], v[124:127]
	v_mfma_f32_16x16x32_bf16 v[116:119], v[166:169], v[190:193], v[116:119]
	v_mfma_f32_16x16x32_bf16 v[108:111], v[158:161], v[198:201], v[108:111]
	v_mfma_f32_16x16x32_bf16 v[100:103], v[166:169], v[198:201], v[100:103]
	v_mfma_f32_16x16x32_bf16 v[92:95], v[158:161], v[206:209], v[92:95]
	v_mfma_f32_16x16x32_bf16 v[84:87], v[166:169], v[206:209], v[84:87]
	v_mfma_f32_16x16x32_bf16 v[76:79], v[158:161], v[214:217], v[76:79]
	v_mfma_f32_16x16x32_bf16 v[68:71], v[166:169], v[214:217], v[68:71]
	s_setprio 0
	s_setprio 1
	v_mfma_f32_16x16x32_bf16 v[120:123], v[170:173], v[186:189], v[120:123]
	v_mfma_f32_16x16x32_bf16 v[112:115], v[178:181], v[186:189], v[112:115]
	v_mfma_f32_16x16x32_bf16 v[104:107], v[170:173], v[194:197], v[104:107]
	v_mfma_f32_16x16x32_bf16 v[96:99], v[178:181], v[194:197], v[96:99]
	v_mfma_f32_16x16x32_bf16 v[88:91], v[170:173], v[202:205], v[88:91]
	v_mfma_f32_16x16x32_bf16 v[80:83], v[178:181], v[202:205], v[80:83]
	v_mfma_f32_16x16x32_bf16 v[72:75], v[170:173], v[210:213], v[72:75]
	v_mfma_f32_16x16x32_bf16 v[64:67], v[178:181], v[210:213], v[64:67]
	v_mfma_f32_16x16x32_bf16 v[120:123], v[174:177], v[190:193], v[120:123]
	v_mfma_f32_16x16x32_bf16 v[112:115], v[182:185], v[190:193], v[112:115]
	v_mfma_f32_16x16x32_bf16 v[104:107], v[174:177], v[198:201], v[104:107]
	v_mfma_f32_16x16x32_bf16 v[96:99], v[182:185], v[198:201], v[96:99]
	v_mfma_f32_16x16x32_bf16 v[88:91], v[174:177], v[206:209], v[88:91]
	v_mfma_f32_16x16x32_bf16 v[80:83], v[182:185], v[206:209], v[80:83]
	v_mfma_f32_16x16x32_bf16 v[72:75], v[174:177], v[214:217], v[72:75]
	v_mfma_f32_16x16x32_bf16 v[64:67], v[182:185], v[214:217], v[64:67]
	s_setprio 0
	s_barrier
; #define PG8_STAGE(bufoff, gbase, voff) do { _Pragma("unroll") for (int _i = 0; _i < 2; ++_i) \
;         __builtin_amdgcn_global_load_lds((const unsigned*)((const char*)(gbase) + (voff)[_i]), (PG8_LAS unsigned*)(lds + (bufoff) + ldsw + _i * 8192), 16, 0, 0); } while (0)
; #define PG8_LDA(dst, b, h) do { _Pragma("unroll") for (int m = 0; m < 4; ++m) _Pragma("unroll") for (int k = 0; k < 2; ++k) dst[m][k] = *(const PG8_LAS bf16x8*)(lds + PG8_SA(b, h) + aoff + m * 2048 + k * 1024); } while (0)
; #define PG8_LDB(dst, b, h) do { _Pragma("unroll") for (int n = 0; n < 2; ++n) _Pragma("unroll") for (int k = 0; k < 2; ++k) dst[n][k] = *(const PG8_LAS bf16x8*)(lds + PG8_SB(b, h) + boff + n * 2048 + k * 1024); } while (0)
; template <class Epi, class Sched, bool ALIGN_EPI = false, bool SP2 = false>
; __device__ __forceinline__ void gemm_phase(PG8_LAS unsigned char* lds, const Gemm g, const Sched& S, const Epi& E) {
;     ...
;         for (int t = 0; t < nt; t += 2) {
;             const bool last = (t == nt - 2);
;             const char* a1 = cA + (size_t)(t + 1) * kstep;
;             const char* a2 = last ? nA : cA + (size_t)(t + 2) * kstep; const char* b2 = last ? nB : cB + (size_t)(t + 2) * kstep;
;             const char* a3 = a2 + kstep; const char* b3 = b2 + kstep;
;             if (last && has_next) S.a_ready(nxt);
;             if constexpr (SP2) {
;             PG8_LDB(B0, 0, 0); PG8_LDB(B1, 0, 1); PG8_SCHED; PG8_LDA(At, 0, 0); PG8_STAGE(PG8_SA(1, 1), a1 + hstep, voffA);
;             PG8_WAIT_V(8); PG8_WAIT_L(0); PG8_BAR; PG8_MMA(0, 0, At, B0); PG8_MMA(0, 1, At, B1); PG8_BAR; PG8_SCHED;
;             PG8_LDA(At, 0, 1); PG8_STAGE(PG8_SB(0, 0), b2, voffB); PG8_STAGE(PG8_SB(0, 1), b2 + hstep, voffB); PG8_STAGE(PG8_SA(0, 0), a2, voffA);
;             PG8_WAIT_V(8); PG8_WAIT_L(0); PG8_BAR; PG8_MMA(1, 0, At, B0); PG8_MMA(1, 1, At, B1); PG8_BAR; PG8_SCHED;
;             PG8_LDB(B0, 1, 0); PG8_LDB(B1, 1, 1); PG8_SCHED; PG8_LDA(At, 1, 0); PG8_STAGE(PG8_SA(0, 1), a2 + hstep, voffA);
;             PG8_WAIT_V(8); PG8_WAIT_L(0); PG8_BAR; PG8_MMA(0, 0, At, B0); PG8_MMA(0, 1, At, B1); PG8_BAR; PG8_SCHED;
;             PG8_LDA(At, 1, 1); PG8_STAGE(PG8_SB(1, 0), b3, voffB); PG8_STAGE(PG8_SB(1, 1), b3 + hstep, voffB); PG8_STAGE(PG8_SA(1, 0), a3, voffA);
;             PG8_WAIT_V(8); PG8_WAIT_L(0); PG8_BAR; PG8_MMA(1, 0, At, B0); PG8_MMA(1, 1, At, B1); PG8_BAR; PG8_SCHED;
	s_add_i32 s33, s33, s52
	v_lshl_add_u64 v[150:151], v[150:151], 0, s[10:11]
	s_mov_b32 m0, s33
	ds_read_b128 v[186:189], v149 offset:49152
	ds_read_b128 v[190:193], v149 offset:50176
	ds_read_b128 v[194:197], v149 offset:51200
	ds_read_b128 v[198:201], v149 offset:52224
	ds_read_b128 v[202:205], v149 offset:53248
	ds_read_b128 v[206:209], v149 offset:54272
	ds_read_b128 v[210:213], v149 offset:55296
	ds_read_b128 v[214:217], v149 offset:56320
	global_load_lds_dwordx4 v[150:151], off
	s_add_i32 m0, s33, 0x2000
	s_add_u32 s42, s42, 0x40080
	v_lshl_add_u64 v[150:151], v[218:219], 0, s[10:11]
	s_addc_u32 s43, s43, 0
	s_add_i32 s33, s34, s52
	global_load_lds_dwordx4 v[150:151], off
	v_lshl_add_u64 v[150:151], s[42:43], 0, v[130:131]
	s_mov_b32 m0, s33
	s_nop 0
	global_load_lds_dwordx4 v[150:151], off
	v_lshl_add_u64 v[150:151], s[42:43], 0, v[134:135]
	s_add_i32 m0, s33, 0x2000
	s_nop 0
	global_load_lds_dwordx4 v[150:151], off
	v_lshl_add_u64 v[150:151], v[220:221], 0, s[10:11]
	s_mov_b32 m0, s60
	s_nop 0
	global_load_lds_dwordx4 v[150:151], off
	v_lshl_add_u64 v[150:151], v[222:223], 0, s[10:11]
	s_mov_b32 m0, s61
	s_nop 0
	global_load_lds_dwordx4 v[150:151], off
	s_waitcnt vmcnt(8)
	s_waitcnt lgkmcnt(0)
	s_barrier
	s_setprio 1
	s_waitcnt lgkmcnt(0)
	v_mfma_f32_16x16x32_bf16 v[60:63], v[154:157], v[186:189], v[60:63]
	v_mfma_f32_16x16x32_bf16 v[52:55], v[162:165], v[186:189], v[52:55]
	v_mfma_f32_16x16x32_bf16 v[44:47], v[154:157], v[194:197], v[44:47]
	v_mfma_f32_16x16x32_bf16 v[36:39], v[162:165], v[194:197], v[36:39]
	v_mfma_f32_16x16x32_bf16 v[28:31], v[154:157], v[202:205], v[28:31]
	v_mfma_f32_16x16x32_bf16 v[20:23], v[162:165], v[202:205], v[20:23]
	v_mfma_f32_16x16x32_bf16 v[12:15], v[154:157], v[210:213], v[12:15]
	v_mfma_f32_16x16x32_bf16 v[4:7], v[162:165], v[210:213], v[4:7]
	v_mfma_f32_16x16x32_bf16 v[60:63], v[158:161], v[190:193], v[60:63]
	v_mfma_f32_16x16x32_bf16 v[52:55], v[166:169], v[190:193], v[52:55]
	v_mfma_f32_16x16x32_bf16 v[44:47], v[158:161], v[198:201], v[44:47]
	v_mfma_f32_16x16x32_bf16 v[36:39], v[166:169], v[198:201], v[36:39]
	v_mfma_f32_16x16x32_bf16 v[28:31], v[158:161], v[206:209], v[28:31]
	v_mfma_f32_16x16x32_bf16 v[20:23], v[166:169], v[206:209], v[20:23]
	v_mfma_f32_16x16x32_bf16 v[12:15], v[158:161], v[214:217], v[12:15]
	v_mfma_f32_16x16x32_bf16 v[4:7], v[166:169], v[214:217], v[4:7]
	s_setprio 0
	s_setprio 1
	v_mfma_f32_16x16x32_bf16 v[56:59], v[170:173], v[186:189], v[56:59]
	v_mfma_f32_16x16x32_bf16 v[48:51], v[178:181], v[186:189], v[48:51]
	v_mfma_f32_16x16x32_bf16 v[40:43], v[170:173], v[194:197], v[40:43]
	v_mfma_f32_16x16x32_bf16 v[32:35], v[178:181], v[194:197], v[32:35]
	v_mfma_f32_16x16x32_bf16 v[24:27], v[170:173], v[202:205], v[24:27]
	v_mfma_f32_16x16x32_bf16 v[16:19], v[178:181], v[202:205], v[16:19]
	v_mfma_f32_16x16x32_bf16 v[8:11], v[170:173], v[210:213], v[8:11]
	v_mfma_f32_16x16x32_bf16 v[0:3], v[178:181], v[210:213], v[0:3]
	v_mfma_f32_16x16x32_bf16 v[56:59], v[174:177], v[190:193], v[56:59]
	v_mfma_f32_16x16x32_bf16 v[48:51], v[182:185], v[190:193], v[48:51]
	v_mfma_f32_16x16x32_bf16 v[40:43], v[174:177], v[198:201], v[40:43]
	v_mfma_f32_16x16x32_bf16 v[32:35], v[182:185], v[198:201], v[32:35]
	v_mfma_f32_16x16x32_bf16 v[24:27], v[174:177], v[206:209], v[24:27]
	v_mfma_f32_16x16x32_bf16 v[16:19], v[182:185], v[206:209], v[16:19]
	v_mfma_f32_16x16x32_bf16 v[8:11], v[174:177], v[214:217], v[8:11]
	v_mfma_f32_16x16x32_bf16 v[0:3], v[182:185], v[214:217], v[0:3]
	s_setprio 0
	s_barrier
	s_mov_b32 s32, 0
	s_add_i32 s76, s76, 2
	s_add_u32 s40, s40, 0x100
	s_addc_u32 s41, s41, 0
	s_add_u32 s74, s74, 0x100
	s_addc_u32 s75, s75, 0
	s_cmp_gt_u32 s76, 13
	s_cbranch_scc0 .LBB0_714
	s_and_b64 vcc, exec, s[12:13]
	s_cbranch_vccz .LBB0_717
	s_barrier

; #define PG8_STAGE(bufoff, gbase, voff) do { _Pragma("unroll") for (int _i = 0; _i < 2; ++_i) \
;         __builtin_amdgcn_global_load_lds((const unsigned*)((const char*)(gbase) + (voff)[_i]), (PG8_LAS unsigned*)(lds + (bufoff) + ldsw + _i * 8192), 16, 0, 0); } while (0)
; #define PG8_LDA(dst, b, h) do { _Pragma("unroll") for (int m = 0; m < 4; ++m) _Pragma("unroll") for (int k = 0; k < 2; ++k) dst[m][k] = *(const PG8_LAS bf16x8*)(lds + PG8_SA(b, h) + aoff + m * 2048 + k * 1024); } while (0)
; #define PG8_LDB(dst, b, h) do { _Pragma("unroll") for (int n = 0; n < 2; ++n) _Pragma("unroll") for (int k = 0; k < 2; ++k) dst[n][k] = *(const PG8_LAS bf16x8*)(lds + PG8_SB(b, h) + boff + n * 2048 + k * 1024); } while (0)
; #define PG8_SCHED __builtin_amdgcn_sched_barrier(0)
; template <class Epi, class Sched, bool ALIGN_EPI = false, bool SP2 = false>
; __device__ __forceinline__ void gemm_phase(PG8_LAS unsigned char* lds, const Gemm g, const Sched& S, const Epi& E) {
;     ...
;     for (;;) {
;         const bool has_next = S.next(ui + 1, nxt);
;         const char* nA = has_next ? (const char*)g.A + (size_t)nxt.pm * tstep : cA; const char* nB = has_next ? (const char*)g.Bt + (size_t)nxt.pn * tstep : cB;
;         for (int t = 0; t < nt; t += 2) {
;             const bool last = (t == nt - 2);
;             const char* a1 = cA + (size_t)(t + 1) * kstep;
;             const char* a2 = last ? nA : cA + (size_t)(t + 2) * kstep; const char* b2 = last ? nB : cB + (size_t)(t + 2) * kstep;
;             const char* a3 = a2 + kstep; const char* b3 = b2 + kstep;
;             if (last && has_next) S.a_ready(nxt);
;             if constexpr (SP2) {
;             PG8_LDB(B0, 0, 0); PG8_LDB(B1, 0, 1); PG8_SCHED; PG8_LDA(At, 0, 0); PG8_STAGE(PG8_SA(1, 1), a1 + hstep, voffA);
;     ...
;         for (int a = 0; a < 2; ++a)
; #pragma unroll
;             for (int b = 0; b < 2; ++b)
; #pragma unroll
;                 for (int m = 0; m < 4; ++m)
; #pragma unroll
;                     for (int n = 0; n < 2; ++n) acc[a][b][m][n] = (f32x4){0.f, 0.f, 0.f, 0.f};
.LBB0_1341:
	s_ashr_i32 s19, s18, 31
	s_lshl_b64 s[20:21], s[18:19], 19
	s_add_u32 s20, s16, s20
	s_addc_u32 s21, s17, s21
	s_and_b64 s[22:23], s[0:1], exec
	s_cselect_b32 s19, s21, s37
	s_cselect_b32 s58, s20, s36
	s_ashr_i32 s15, s14, 31
	s_lshl_b64 s[22:23], s[14:15], 19
	s_add_u32 s22, s42, s22
	s_addc_u32 s23, s43, s23
	s_and_b64 s[40:41], s[0:1], exec
	s_cselect_b32 s15, s23, s39
	s_cselect_b32 s59, s22, s38
	s_add_u32 s36, s36, 0x40080
	s_addc_u32 s37, s37, 0
	s_add_u32 s60, s38, 0x100
	v_mov_b32_e32 v0, 0
	s_addc_u32 s61, s39, 0
	s_mov_b32 s62, -2
	s_cmp_gt_u32 s50, 1
	s_cselect_b32 s32, 1, 0
	v_mov_b32_e32 v1, v0
	v_mov_b32_e32 v2, v0
	v_mov_b32_e32 v3, v0
	v_mov_b32_e32 v8, v0
	v_mov_b32_e32 v9, v0
	v_mov_b32_e32 v10, v0
	v_mov_b32_e32 v11, v0
	v_mov_b32_e32 v16, v0
	v_mov_b32_e32 v17, v0
	v_mov_b32_e32 v18, v0
	v_mov_b32_e32 v19, v0
	v_mov_b32_e32 v24, v0
	v_mov_b32_e32 v25, v0
	v_mov_b32_e32 v26, v0
	v_mov_b32_e32 v27, v0
	v_mov_b32_e32 v32, v0
	v_mov_b32_e32 v33, v0
	v_mov_b32_e32 v34, v0
	v_mov_b32_e32 v35, v0
	v_mov_b32_e32 v40, v0
	v_mov_b32_e32 v41, v0
	v_mov_b32_e32 v42, v0
	v_mov_b32_e32 v43, v0
	v_mov_b32_e32 v48, v0
	v_mov_b32_e32 v49, v0
	v_mov_b32_e32 v50, v0
	v_mov_b32_e32 v51, v0
	v_mov_b32_e32 v56, v0
	v_mov_b32_e32 v57, v0
	v_mov_b32_e32 v58, v0
	v_mov_b32_e32 v59, v0
	v_mov_b32_e32 v4, v0
	v_mov_b32_e32 v5, v0
	v_mov_b32_e32 v6, v0
	v_mov_b32_e32 v7, v0
	v_mov_b32_e32 v12, v0
	v_mov_b32_e32 v13, v0
	v_mov_b32_e32 v14, v0
	v_mov_b32_e32 v15, v0
	v_mov_b32_e32 v20, v0
	v_mov_b32_e32 v21, v0
	s_waitcnt lgkmcnt(0)
	v_mov_b32_e32 v22, v0
	v_mov_b32_e32 v23, v0
	v_mov_b32_e32 v28, v0
	v_mov_b32_e32 v29, v0
	v_mov_b32_e32 v30, v0
	v_mov_b32_e32 v31, v0
	v_mov_b32_e32 v36, v0
	v_mov_b32_e32 v37, v0
	v_mov_b32_e32 v38, v0
	v_mov_b32_e32 v39, v0
	v_mov_b32_e32 v44, v0
	v_mov_b32_e32 v45, v0
	v_mov_b32_e32 v46, v0
	v_mov_b32_e32 v47, v0
	v_mov_b32_e32 v52, v0
	v_mov_b32_e32 v53, v0
	v_mov_b32_e32 v54, v0
	v_mov_b32_e32 v55, v0
	v_mov_b32_e32 v60, v0
	v_mov_b32_e32 v61, v0
	v_mov_b32_e32 v62, v0
	v_mov_b32_e32 v63, v0
	v_mov_b32_e32 v64, v0
	v_mov_b32_e32 v65, v0
	v_mov_b32_e32 v66, v0
	v_mov_b32_e32 v67, v0
	v_mov_b32_e32 v72, v0
	v_mov_b32_e32 v73, v0
	v_mov_b32_e32 v74, v0
	v_mov_b32_e32 v75, v0
	v_mov_b32_e32 v80, v0
	v_mov_b32_e32 v81, v0
	v_mov_b32_e32 v82, v0
	v_mov_b32_e32 v83, v0
	v_mov_b32_e32 v88, v0
	v_mov_b32_e32 v89, v0
	v_mov_b32_e32 v90, v0
	v_mov_b32_e32 v91, v0
	v_mov_b32_e32 v96, v0
	v_mov_b32_e32 v97, v0
	v_mov_b32_e32 v98, v0
	v_mov_b32_e32 v99, v0
	v_mov_b32_e32 v104, v0
	v_mov_b32_e32 v105, v0
	v_mov_b32_e32 v106, v0
	v_mov_b32_e32 v107, v0
	v_mov_b32_e32 v112, v0
	v_mov_b32_e32 v113, v0
	v_mov_b32_e32 v114, v0
	v_mov_b32_e32 v115, v0
	v_mov_b32_e32 v120, v0
	v_mov_b32_e32 v121, v0
	v_mov_b32_e32 v122, v0
	v_mov_b32_e32 v123, v0
	v_mov_b32_e32 v68, v0
	v_mov_b32_e32 v69, v0
	v_mov_b32_e32 v70, v0
	v_mov_b32_e32 v71, v0
	v_mov_b32_e32 v76, v0
	v_mov_b32_e32 v77, v0
	v_mov_b32_e32 v78, v0
	v_mov_b32_e32 v79, v0
	v_mov_b32_e32 v84, v0
	v_mov_b32_e32 v85, v0
	v_mov_b32_e32 v86, v0
	v_mov_b32_e32 v87, v0
	v_mov_b32_e32 v92, v0
	v_mov_b32_e32 v93, v0
	v_mov_b32_e32 v94, v0
	v_mov_b32_e32 v95, v0
	v_mov_b32_e32 v100, v0
	v_mov_b32_e32 v101, v0
	v_mov_b32_e32 v102, v0
	v_mov_b32_e32 v103, v0
	v_mov_b32_e32 v108, v0
	v_mov_b32_e32 v109, v0
	v_mov_b32_e32 v110, v0
	v_mov_b32_e32 v111, v0
	v_mov_b32_e32 v116, v0
	v_mov_b32_e32 v117, v0
	v_mov_b32_e32 v118, v0
	v_mov_b32_e32 v119, v0
	v_mov_b32_e32 v124, v0
	v_mov_b32_e32 v125, v0
	v_mov_b32_e32 v126, v0
	v_mov_b32_e32 v127, v0
.LBB0_1342:
	ds_read_b128 v[154:157], v147
	ds_read_b128 v[158:161], v147 offset:1024
	ds_read_b128 v[162:165], v147 offset:2048
	ds_read_b128 v[166:169], v147 offset:3072
	ds_read_b128 v[170:173], v148
	ds_read_b128 v[174:177], v148 offset:1024
	ds_read_b128 v[178:181], v148 offset:2048
	ds_read_b128 v[182:185], v148 offset:3072
	s_add_u32 s33, s36, 0xfffc0080
	s_addc_u32 s34, s37, -1
	s_cmp_eq_u32 s62, 12
	s_cselect_b32 s41, s19, s34
	s_cselect_b32 s40, s58, s33
	s_cselect_b32 s39, s15, s61
	s_cselect_b32 s38, s59, s60
	v_lshl_add_u64 v[150:151], s[36:37], 0, v[136:137]
	s_add_i32 m0, s25, 0xc000
	ds_read_b128 v[186:189], v149
	ds_read_b128 v[190:193], v149 offset:1024
	ds_read_b128 v[194:197], v149 offset:2048
	ds_read_b128 v[198:201], v149 offset:3072
	ds_read_b128 v[202:205], v149 offset:4096
	ds_read_b128 v[206:209], v149 offset:5120
	ds_read_b128 v[210:213], v149 offset:6144
	ds_read_b128 v[214:217], v149 offset:7168
	global_load_lds_dwordx4 v[150:151], off
	v_lshl_add_u64 v[150:151], s[36:37], 0, v[138:139]
	s_add_i32 m0, s25, 0xe000
	s_nop 0
	global_load_lds_dwordx4 v[150:151], off
	s_cmp_eq_u32 s32, 0
	s_cbranch_scc1 .Lrw8_p15_0
	s_waitcnt vmcnt(16)
	s_branch .Lrwd_p15_0

; #define PG8_STAGE(bufoff, gbase, voff) do { _Pragma("unroll") for (int _i = 0; _i < 2; ++_i) \
;         __builtin_amdgcn_global_load_lds((const unsigned*)((const char*)(gbase) + (voff)[_i]), (PG8_LAS unsigned*)(lds + (bufoff) + ldsw + _i * 8192), 16, 0, 0); } while (0)
; #define PG8_LDA(dst, b, h) do { _Pragma("unroll") for (int m = 0; m < 4; ++m) _Pragma("unroll") for (int k = 0; k < 2; ++k) dst[m][k] = *(const PG8_LAS bf16x8*)(lds + PG8_SA(b, h) + aoff + m * 2048 + k * 1024); } while (0)
; #define PG8_LDB(dst, b, h) do { _Pragma("unroll") for (int n = 0; n < 2; ++n) _Pragma("unroll") for (int k = 0; k < 2; ++k) dst[n][k] = *(const PG8_LAS bf16x8*)(lds + PG8_SB(b, h) + boff + n * 2048 + k * 1024); } while (0)
; #define PG8_MMA(ai, bj, At, Bt) do { __builtin_amdgcn_s_setprio(1); _Pragma("unroll") for (int m = 0; m < 4; ++m) _Pragma("unroll") for (int n = 0; n < 2; ++n) _Pragma("unroll") for (int k = 0; k < 2; ++k) \
;         acc[ai][bj][m][n] = __builtin_amdgcn_mfma_f32_16x16x32_bf16(Bt[n][k], At[m][k], acc[ai][bj][m][n], 0, 0, 0); __builtin_amdgcn_s_setprio(0); } while (0)
; #define PG8_WAIT_V(n) asm volatile("s_waitcnt vmcnt(" #n ")" ::: "memory")
; #define PG8_WAIT_L(n) asm volatile("s_waitcnt lgkmcnt(" #n ")" ::: "memory")
; #define PG8_BAR __builtin_amdgcn_s_barrier()
; #define PG8_SCHED __builtin_amdgcn_sched_barrier(0)
; template <class Epi, class Sched, bool ALIGN_EPI = false, bool SP2 = false>
; __device__ __forceinline__ void gemm_phase(PG8_LAS unsigned char* lds, const Gemm g, const Sched& S, const Epi& E) {
;     ...
;             PG8_LDB(B0, 0, 0); PG8_LDB(B1, 0, 1); PG8_SCHED; PG8_LDA(At, 0, 0); PG8_STAGE(PG8_SA(1, 1), a1 + hstep, voffA);
;             PG8_WAIT_V(8); PG8_WAIT_L(0); PG8_BAR; PG8_MMA(0, 0, At, B0); PG8_MMA(0, 1, At, B1); PG8_BAR; PG8_SCHED;
;             PG8_LDA(At, 0, 1); PG8_STAGE(PG8_SB(0, 0), b2, voffB); PG8_STAGE(PG8_SB(0, 1), b2 + hstep, voffB); PG8_STAGE(PG8_SA(0, 0), a2, voffA);
.Lrwd_p15_0:
	s_waitcnt lgkmcnt(0)
	s_barrier
	s_setprio 1
	s_waitcnt lgkmcnt(0)
	v_mfma_f32_16x16x32_bf16 v[124:127], v[154:157], v[186:189], v[124:127]
	v_mfma_f32_16x16x32_bf16 v[116:119], v[162:165], v[186:189], v[116:119]
	v_mfma_f32_16x16x32_bf16 v[108:111], v[154:157], v[194:197], v[108:111]
	v_mfma_f32_16x16x32_bf16 v[100:103], v[162:165], v[194:197], v[100:103]
	v_mfma_f32_16x16x32_bf16 v[92:95], v[154:157], v[202:205], v[92:95]
	v_mfma_f32_16x16x32_bf16 v[84:87], v[162:165], v[202:205], v[84:87]
	v_mfma_f32_16x16x32_bf16 v[76:79], v[154:157], v[210:213], v[76:79]
	v_mfma_f32_16x16x32_bf16 v[68:71], v[162:165], v[210:213], v[68:71]
	v_mfma_f32_16x16x32_bf16 v[124:127], v[158:161], v[190:193], v[124:127]
	v_mfma_f32_16x16x32_bf16 v[116:119], v[166:169], v[190:193], v[116:119]
	v_mfma_f32_16x16x32_bf16 v[108:111], v[158:161], v[198:201], v[108:111]
	v_mfma_f32_16x16x32_bf16 v[100:103], v[166:169], v[198:201], v[100:103]
	v_mfma_f32_16x16x32_bf16 v[92:95], v[158:161], v[206:209], v[92:95]
	v_mfma_f32_16x16x32_bf16 v[84:87], v[166:169], v[206:209], v[84:87]
	v_mfma_f32_16x16x32_bf16 v[76:79], v[158:161], v[214:217], v[76:79]
	v_mfma_f32_16x16x32_bf16 v[68:71], v[166:169], v[214:217], v[68:71]
	s_setprio 0
	s_setprio 1
	v_mfma_f32_16x16x32_bf16 v[120:123], v[170:173], v[186:189], v[120:123]
	v_mfma_f32_16x16x32_bf16 v[112:115], v[178:181], v[186:189], v[112:115]
	v_mfma_f32_16x16x32_bf16 v[104:107], v[170:173], v[194:197], v[104:107]
	v_mfma_f32_16x16x32_bf16 v[96:99], v[178:181], v[194:197], v[96:99]
	v_mfma_f32_16x16x32_bf16 v[88:91], v[170:173], v[202:205], v[88:91]
	v_mfma_f32_16x16x32_bf16 v[80:83], v[178:181], v[202:205], v[80:83]
	v_mfma_f32_16x16x32_bf16 v[72:75], v[170:173], v[210:213], v[72:75]
	v_mfma_f32_16x16x32_bf16 v[64:67], v[178:181], v[210:213], v[64:67]
	v_mfma_f32_16x16x32_bf16 v[120:123], v[174:177], v[190:193], v[120:123]
	v_mfma_f32_16x16x32_bf16 v[112:115], v[182:185], v[190:193], v[112:115]
	v_mfma_f32_16x16x32_bf16 v[104:107], v[174:177], v[198:201], v[104:107]
	v_mfma_f32_16x16x32_bf16 v[96:99], v[182:185], v[198:201], v[96:99]
	v_mfma_f32_16x16x32_bf16 v[88:91], v[174:177], v[206:209], v[88:91]
	v_mfma_f32_16x16x32_bf16 v[80:83], v[182:185], v[206:209], v[80:83]
	v_mfma_f32_16x16x32_bf16 v[72:75], v[174:177], v[214:217], v[72:75]
	v_mfma_f32_16x16x32_bf16 v[64:67], v[182:185], v[214:217], v[64:67]
	s_setprio 0
	s_barrier
	s_add_i32 s33, s54, s44
	v_lshl_add_u64 v[150:151], s[38:39], 0, v[130:131]
	s_mov_b32 m0, s33
	ds_read_b128 v[186:189], v149 offset:16384
	ds_read_b128 v[190:193], v149 offset:17408
	ds_read_b128 v[194:197], v149 offset:18432
	ds_read_b128 v[198:201], v149 offset:19456
	ds_read_b128 v[202:205], v149 offset:20480
	ds_read_b128 v[206:209], v149 offset:21504
	ds_read_b128 v[210:213], v149 offset:22528
	ds_read_b128 v[214:217], v149 offset:23552
	global_load_lds_dwordx4 v[150:151], off
	s_add_i32 m0, s33, 0x2000
	s_add_u32 s64, s38, 0x40000
	v_lshl_add_u64 v[218:219], s[38:39], 0, v[134:135]
	s_addc_u32 s65, s39, 0
	s_add_i32 s33, s55, s44
	global_load_lds_dwordx4 v[218:219], off
	v_lshl_add_u64 v[220:221], s[64:65], 0, v[130:131]
	s_mov_b32 m0, s33
	v_lshl_add_u64 v[222:223], s[40:41], 0, v[132:133]
	global_load_lds_dwordx4 v[220:221], off
	v_lshl_add_u64 v[220:221], s[64:65], 0, v[134:135]
	s_add_i32 m0, s33, 0x2000
	s_nop 0
	global_load_lds_dwordx4 v[220:221], off
	v_lshl_add_u64 v[220:221], s[40:41], 0, v[128:129]
	s_mov_b32 m0, s25
	s_nop 0
	global_load_lds_dwordx4 v[220:221], off
	s_mov_b32 m0, s47
	s_nop 0
	global_load_lds_dwordx4 v[222:223], off
	s_cmp_eq_u32 s32, 0
	s_cbranch_scc1 .Lrw8_p15_1
	s_waitcnt vmcnt(16)
	s_branch .Lrwd_p15_1

; #define PG8_STAGE(bufoff, gbase, voff) do { _Pragma("unroll") for (int _i = 0; _i < 2; ++_i) \
;         __builtin_amdgcn_global_load_lds((const unsigned*)((const char*)(gbase) + (voff)[_i]), (PG8_LAS unsigned*)(lds + (bufoff) + ldsw + _i * 8192), 16, 0, 0); } while (0)
; #define PG8_LDA(dst, b, h) do { _Pragma("unroll") for (int m = 0; m < 4; ++m) _Pragma("unroll") for (int k = 0; k < 2; ++k) dst[m][k] = *(const PG8_LAS bf16x8*)(lds + PG8_SA(b, h) + aoff + m * 2048 + k * 1024); } while (0)
; #define PG8_LDB(dst, b, h) do { _Pragma("unroll") for (int n = 0; n < 2; ++n) _Pragma("unroll") for (int k = 0; k < 2; ++k) dst[n][k] = *(const PG8_LAS bf16x8*)(lds + PG8_SB(b, h) + boff + n * 2048 + k * 1024); } while (0)
; #define PG8_MMA(ai, bj, At, Bt) do { __builtin_amdgcn_s_setprio(1); _Pragma("unroll") for (int m = 0; m < 4; ++m) _Pragma("unroll") for (int n = 0; n < 2; ++n) _Pragma("unroll") for (int k = 0; k < 2; ++k) \
;         acc[ai][bj][m][n] = __builtin_amdgcn_mfma_f32_16x16x32_bf16(Bt[n][k], At[m][k], acc[ai][bj][m][n], 0, 0, 0); __builtin_amdgcn_s_setprio(0); } while (0)
; #define PG8_WAIT_V(n) asm volatile("s_waitcnt vmcnt(" #n ")" ::: "memory")
; #define PG8_WAIT_L(n) asm volatile("s_waitcnt lgkmcnt(" #n ")" ::: "memory")
; #define PG8_BAR __builtin_amdgcn_s_barrier()
; #define PG8_SCHED __builtin_amdgcn_sched_barrier(0)
; template <class Epi, class Sched, bool ALIGN_EPI = false, bool SP2 = false>
; __device__ __forceinline__ void gemm_phase(PG8_LAS unsigned char* lds, const Gemm g, const Sched& S, const Epi& E) {
;     ...
;             PG8_WAIT_V(8); PG8_WAIT_L(0); PG8_BAR; PG8_MMA(1, 0, At, B0); PG8_MMA(1, 1, At, B1); PG8_BAR; PG8_SCHED;
;             PG8_LDB(B0, 1, 0); PG8_LDB(B1, 1, 1); PG8_SCHED; PG8_LDA(At, 1, 0); PG8_STAGE(PG8_SA(0, 1), a2 + hstep, voffA);
;             PG8_WAIT_V(8); PG8_WAIT_L(0); PG8_BAR; PG8_MMA(0, 0, At, B0); PG8_MMA(0, 1, At, B1); PG8_BAR; PG8_SCHED;
.Lrwd_p15_1:
	s_waitcnt lgkmcnt(0)
	s_barrier
	s_setprio 1
	s_waitcnt lgkmcnt(0)
	v_mfma_f32_16x16x32_bf16 v[60:63], v[154:157], v[186:189], v[60:63]
	v_mfma_f32_16x16x32_bf16 v[52:55], v[162:165], v[186:189], v[52:55]
	v_mfma_f32_16x16x32_bf16 v[44:47], v[154:157], v[194:197], v[44:47]
	v_mfma_f32_16x16x32_bf16 v[36:39], v[162:165], v[194:197], v[36:39]
	v_mfma_f32_16x16x32_bf16 v[28:31], v[154:157], v[202:205], v[28:31]
	v_mfma_f32_16x16x32_bf16 v[20:23], v[162:165], v[202:205], v[20:23]
	v_mfma_f32_16x16x32_bf16 v[12:15], v[154:157], v[210:213], v[12:15]
	v_mfma_f32_16x16x32_bf16 v[4:7], v[162:165], v[210:213], v[4:7]
	v_mfma_f32_16x16x32_bf16 v[60:63], v[158:161], v[190:193], v[60:63]
	v_mfma_f32_16x16x32_bf16 v[52:55], v[166:169], v[190:193], v[52:55]
	v_mfma_f32_16x16x32_bf16 v[44:47], v[158:161], v[198:201], v[44:47]
	v_mfma_f32_16x16x32_bf16 v[36:39], v[166:169], v[198:201], v[36:39]
	v_mfma_f32_16x16x32_bf16 v[28:31], v[158:161], v[206:209], v[28:31]
	v_mfma_f32_16x16x32_bf16 v[20:23], v[166:169], v[206:209], v[20:23]
	v_mfma_f32_16x16x32_bf16 v[12:15], v[158:161], v[214:217], v[12:15]
	v_mfma_f32_16x16x32_bf16 v[4:7], v[166:169], v[214:217], v[4:7]
	s_setprio 0
	s_setprio 1
	v_mfma_f32_16x16x32_bf16 v[56:59], v[170:173], v[186:189], v[56:59]
	v_mfma_f32_16x16x32_bf16 v[48:51], v[178:181], v[186:189], v[48:51]
	v_mfma_f32_16x16x32_bf16 v[40:43], v[170:173], v[194:197], v[40:43]
	v_mfma_f32_16x16x32_bf16 v[32:35], v[178:181], v[194:197], v[32:35]
	v_mfma_f32_16x16x32_bf16 v[24:27], v[170:173], v[202:205], v[24:27]
	v_mfma_f32_16x16x32_bf16 v[16:19], v[178:181], v[202:205], v[16:19]
	v_mfma_f32_16x16x32_bf16 v[8:11], v[170:173], v[210:213], v[8:11]
	v_mfma_f32_16x16x32_bf16 v[0:3], v[178:181], v[210:213], v[0:3]
	v_mfma_f32_16x16x32_bf16 v[56:59], v[174:177], v[190:193], v[56:59]
	v_mfma_f32_16x16x32_bf16 v[48:51], v[182:185], v[190:193], v[48:51]
	v_mfma_f32_16x16x32_bf16 v[40:43], v[174:177], v[198:201], v[40:43]
	v_mfma_f32_16x16x32_bf16 v[32:35], v[182:185], v[198:201], v[32:35]
	v_mfma_f32_16x16x32_bf16 v[24:27], v[174:177], v[206:209], v[24:27]
	v_mfma_f32_16x16x32_bf16 v[16:19], v[182:185], v[206:209], v[16:19]
	v_mfma_f32_16x16x32_bf16 v[8:11], v[174:177], v[214:217], v[8:11]
	v_mfma_f32_16x16x32_bf16 v[0:3], v[182:185], v[214:217], v[0:3]
	s_setprio 0
	s_barrier
	s_add_i32 s33, 0, 0x18000
	v_add_u32_e32 v153, s33, v145
	s_add_i32 s34, 0, 0x1c000
	ds_read_b128 v[154:157], v153
	ds_read_b128 v[158:161], v153 offset:1024
	ds_read_b128 v[162:165], v153 offset:2048
	ds_read_b128 v[166:169], v153 offset:3072
	v_add_u32_e32 v153, s34, v145
	ds_read_b128 v[170:173], v153
	ds_read_b128 v[174:177], v153 offset:1024
	ds_read_b128 v[178:181], v153 offset:2048
	ds_read_b128 v[182:185], v153 offset:3072
	s_add_u32 s40, s40, 0x40000
	s_addc_u32 s41, s41, 0
	s_mov_b32 m0, s48
	v_lshl_add_u64 v[224:225], s[40:41], 0, v[128:129]
	ds_read_b128 v[186:189], v149 offset:32768
	ds_read_b128 v[190:193], v149 offset:33792
	ds_read_b128 v[194:197], v149 offset:34816
	ds_read_b128 v[198:201], v149 offset:35840
	ds_read_b128 v[202:205], v149 offset:36864
	ds_read_b128 v[206:209], v149 offset:37888
	ds_read_b128 v[210:213], v149 offset:38912
	ds_read_b128 v[214:217], v149 offset:39936
	global_load_lds_dwordx4 v[224:225], off
	v_lshl_add_u64 v[224:225], s[40:41], 0, v[132:133]
	s_mov_b32 m0, s49
	s_nop 0
	global_load_lds_dwordx4 v[224:225], off
	s_waitcnt vmcnt(8)
	s_waitcnt lgkmcnt(0)
	s_barrier
	s_setprio 1
	s_waitcnt lgkmcnt(0)
	v_mfma_f32_16x16x32_bf16 v[124:127], v[154:157], v[186:189], v[124:127]
	v_mfma_f32_16x16x32_bf16 v[116:119], v[162:165], v[186:189], v[116:119]
	v_mfma_f32_16x16x32_bf16 v[108:111], v[154:157], v[194:197], v[108:111]
	v_mfma_f32_16x16x32_bf16 v[100:103], v[162:165], v[194:197], v[100:103]
	v_mfma_f32_16x16x32_bf16 v[92:95], v[154:157], v[202:205], v[92:95]
	v_mfma_f32_16x16x32_bf16 v[84:87], v[162:165], v[202:205], v[84:87]
	v_mfma_f32_16x16x32_bf16 v[76:79], v[154:157], v[210:213], v[76:79]
	v_mfma_f32_16x16x32_bf16 v[68:71], v[162:165], v[210:213], v[68:71]
	v_mfma_f32_16x16x32_bf16 v[124:127], v[158:161], v[190:193], v[124:127]
	v_mfma_f32_16x16x32_bf16 v[116:119], v[166:169], v[190:193], v[116:119]
	v_mfma_f32_16x16x32_bf16 v[108:111], v[158:161], v[198:201], v[108:111]
	v_mfma_f32_16x16x32_bf16 v[100:103], v[166:169], v[198:201], v[100:103]
	v_mfma_f32_16x16x32_bf16 v[92:95], v[158:161], v[206:209], v[92:95]
	v_mfma_f32_16x16x32_bf16 v[84:87], v[166:169], v[206:209], v[84:87]
	v_mfma_f32_16x16x32_bf16 v[76:79], v[158:161], v[214:217], v[76:79]
	v_mfma_f32_16x16x32_bf16 v[68:71], v[166:169], v[214:217], v[68:71]
	s_setprio 0
	s_setprio 1
	v_mfma_f32_16x16x32_bf16 v[120:123], v[170:173], v[186:189], v[120:123]
	v_mfma_f32_16x16x32_bf16 v[112:115], v[178:181], v[186:189], v[112:115]
	v_mfma_f32_16x16x32_bf16 v[104:107], v[170:173], v[194:197], v[104:107]
	v_mfma_f32_16x16x32_bf16 v[96:99], v[178:181], v[194:197], v[96:99]
	v_mfma_f32_16x16x32_bf16 v[88:91], v[170:173], v[202:205], v[88:91]
	v_mfma_f32_16x16x32_bf16 v[80:83], v[178:181], v[202:205], v[80:83]
	v_mfma_f32_16x16x32_bf16 v[72:75], v[170:173], v[210:213], v[72:75]
	v_mfma_f32_16x16x32_bf16 v[64:67], v[178:181], v[210:213], v[64:67]
	v_mfma_f32_16x16x32_bf16 v[120:123], v[174:177], v[190:193], v[120:123]
	v_mfma_f32_16x16x32_bf16 v[112:115], v[182:185], v[190:193], v[112:115]
	v_mfma_f32_16x16x32_bf16 v[104:107], v[174:177], v[198:201], v[104:107]
	v_mfma_f32_16x16x32_bf16 v[96:99], v[182:185], v[198:201], v[96:99]
	v_mfma_f32_16x16x32_bf16 v[88:91], v[174:177], v[206:209], v[88:91]
	v_mfma_f32_16x16x32_bf16 v[80:83], v[182:185], v[206:209], v[80:83]
	v_mfma_f32_16x16x32_bf16 v[72:75], v[174:177], v[214:217], v[72:75]
	v_mfma_f32_16x16x32_bf16 v[64:67], v[182:185], v[214:217], v[64:67]
	s_setprio 0
	s_barrier
; #define PG8_STAGE(bufoff, gbase, voff) do { _Pragma("unroll") for (int _i = 0; _i < 2; ++_i) \
;         __builtin_amdgcn_global_load_lds((const unsigned*)((const char*)(gbase) + (voff)[_i]), (PG8_LAS unsigned*)(lds + (bufoff) + ldsw + _i * 8192), 16, 0, 0); } while (0)
; #define PG8_LDA(dst, b, h) do { _Pragma("unroll") for (int m = 0; m < 4; ++m) _Pragma("unroll") for (int k = 0; k < 2; ++k) dst[m][k] = *(const PG8_LAS bf16x8*)(lds + PG8_SA(b, h) + aoff + m * 2048 + k * 1024); } while (0)
; #define PG8_LDB(dst, b, h) do { _Pragma("unroll") for (int n = 0; n < 2; ++n) _Pragma("unroll") for (int k = 0; k < 2; ++k) dst[n][k] = *(const PG8_LAS bf16x8*)(lds + PG8_SB(b, h) + boff + n * 2048 + k * 1024); } while (0)
; template <class Epi, class Sched, bool ALIGN_EPI = false, bool SP2 = false>
; __device__ __forceinline__ void gemm_phase(PG8_LAS unsigned char* lds, const Gemm g, const Sched& S, const Epi& E) {
;     ...
;         for (int t = 0; t < nt; t += 2) {
;             const bool last = (t == nt - 2);
;             const char* a1 = cA + (size_t)(t + 1) * kstep;
;             const char* a2 = last ? nA : cA + (size_t)(t + 2) * kstep; const char* b2 = last ? nB : cB + (size_t)(t + 2) * kstep;
;             const char* a3 = a2 + kstep; const char* b3 = b2 + kstep;
;             if (last && has_next) S.a_ready(nxt);
;             if constexpr (SP2) {
;             PG8_LDB(B0, 0, 0); PG8_LDB(B1, 0, 1); PG8_SCHED; PG8_LDA(At, 0, 0); PG8_STAGE(PG8_SA(1, 1), a1 + hstep, voffA);
;             PG8_WAIT_V(8); PG8_WAIT_L(0); PG8_BAR; PG8_MMA(0, 0, At, B0); PG8_MMA(0, 1, At, B1); PG8_BAR; PG8_SCHED;
;             PG8_LDA(At, 0, 1); PG8_STAGE(PG8_SB(0, 0), b2, voffB); PG8_STAGE(PG8_SB(0, 1), b2 + hstep, voffB); PG8_STAGE(PG8_SA(0, 0), a2, voffA);
;             PG8_WAIT_V(8); PG8_WAIT_L(0); PG8_BAR; PG8_MMA(1, 0, At, B0); PG8_MMA(1, 1, At, B1); PG8_BAR; PG8_SCHED;
;             PG8_LDB(B0, 1, 0); PG8_LDB(B1, 1, 1); PG8_SCHED; PG8_LDA(At, 1, 0); PG8_STAGE(PG8_SA(0, 1), a2 + hstep, voffA);
;             PG8_WAIT_V(8); PG8_WAIT_L(0); PG8_BAR; PG8_MMA(0, 0, At, B0); PG8_MMA(0, 1, At, B1); PG8_BAR; PG8_SCHED;
;             PG8_LDA(At, 1, 1); PG8_STAGE(PG8_SB(1, 0), b3, voffB); PG8_STAGE(PG8_SB(1, 1), b3 + hstep, voffB); PG8_STAGE(PG8_SA(1, 0), a3, voffA);
;             PG8_WAIT_V(8); PG8_WAIT_L(0); PG8_BAR; PG8_MMA(1, 0, At, B0); PG8_MMA(1, 1, At, B1); PG8_BAR; PG8_SCHED;
	s_add_i32 s33, s33, s44
	v_lshl_add_u64 v[150:151], v[150:151], 0, s[10:11]
	s_mov_b32 m0, s33
	ds_read_b128 v[186:189], v149 offset:49152
	ds_read_b128 v[190:193], v149 offset:50176
	ds_read_b128 v[194:197], v149 offset:51200
	ds_read_b128 v[198:201], v149 offset:52224
	ds_read_b128 v[202:205], v149 offset:53248
	ds_read_b128 v[206:209], v149 offset:54272
	ds_read_b128 v[210:213], v149 offset:55296
	ds_read_b128 v[214:217], v149 offset:56320
	global_load_lds_dwordx4 v[150:151], off
	s_add_i32 m0, s33, 0x2000
	s_add_u32 s38, s38, 0x40080
	v_lshl_add_u64 v[150:151], v[218:219], 0, s[10:11]
	s_addc_u32 s39, s39, 0
	s_add_i32 s33, s34, s44
	global_load_lds_dwordx4 v[150:151], off
	v_lshl_add_u64 v[150:151], s[38:39], 0, v[130:131]
	s_mov_b32 m0, s33
	s_nop 0
	global_load_lds_dwordx4 v[150:151], off
	v_lshl_add_u64 v[150:151], s[38:39], 0, v[134:135]
	s_add_i32 m0, s33, 0x2000
	s_nop 0
	global_load_lds_dwordx4 v[150:151], off
	v_lshl_add_u64 v[150:151], v[220:221], 0, s[10:11]
	s_mov_b32 m0, s52
	s_nop 0
	global_load_lds_dwordx4 v[150:151], off
	v_lshl_add_u64 v[150:151], v[222:223], 0, s[10:11]
	s_mov_b32 m0, s53
	s_nop 0
	global_load_lds_dwordx4 v[150:151], off
	s_waitcnt vmcnt(8)
	s_waitcnt lgkmcnt(0)
	s_barrier
	s_setprio 1
	s_waitcnt lgkmcnt(0)
	v_mfma_f32_16x16x32_bf16 v[60:63], v[154:157], v[186:189], v[60:63]
	v_mfma_f32_16x16x32_bf16 v[52:55], v[162:165], v[186:189], v[52:55]
	v_mfma_f32_16x16x32_bf16 v[44:47], v[154:157], v[194:197], v[44:47]
	v_mfma_f32_16x16x32_bf16 v[36:39], v[162:165], v[194:197], v[36:39]
	v_mfma_f32_16x16x32_bf16 v[28:31], v[154:157], v[202:205], v[28:31]
	v_mfma_f32_16x16x32_bf16 v[20:23], v[162:165], v[202:205], v[20:23]
	v_mfma_f32_16x16x32_bf16 v[12:15], v[154:157], v[210:213], v[12:15]
	v_mfma_f32_16x16x32_bf16 v[4:7], v[162:165], v[210:213], v[4:7]
	v_mfma_f32_16x16x32_bf16 v[60:63], v[158:161], v[190:193], v[60:63]
	v_mfma_f32_16x16x32_bf16 v[52:55], v[166:169], v[190:193], v[52:55]
	v_mfma_f32_16x16x32_bf16 v[44:47], v[158:161], v[198:201], v[44:47]
	v_mfma_f32_16x16x32_bf16 v[36:39], v[166:169], v[198:201], v[36:39]
	v_mfma_f32_16x16x32_bf16 v[28:31], v[158:161], v[206:209], v[28:31]
	v_mfma_f32_16x16x32_bf16 v[20:23], v[166:169], v[206:209], v[20:23]
	v_mfma_f32_16x16x32_bf16 v[12:15], v[158:161], v[214:217], v[12:15]
	v_mfma_f32_16x16x32_bf16 v[4:7], v[166:169], v[214:217], v[4:7]
	s_setprio 0
	s_setprio 1
	v_mfma_f32_16x16x32_bf16 v[56:59], v[170:173], v[186:189], v[56:59]
	v_mfma_f32_16x16x32_bf16 v[48:51], v[178:181], v[186:189], v[48:51]
	v_mfma_f32_16x16x32_bf16 v[40:43], v[170:173], v[194:197], v[40:43]
	v_mfma_f32_16x16x32_bf16 v[32:35], v[178:181], v[194:197], v[32:35]
	v_mfma_f32_16x16x32_bf16 v[24:27], v[170:173], v[202:205], v[24:27]
	v_mfma_f32_16x16x32_bf16 v[16:19], v[178:181], v[202:205], v[16:19]
	v_mfma_f32_16x16x32_bf16 v[8:11], v[170:173], v[210:213], v[8:11]
	v_mfma_f32_16x16x32_bf16 v[0:3], v[178:181], v[210:213], v[0:3]
	v_mfma_f32_16x16x32_bf16 v[56:59], v[174:177], v[190:193], v[56:59]
	v_mfma_f32_16x16x32_bf16 v[48:51], v[182:185], v[190:193], v[48:51]
	v_mfma_f32_16x16x32_bf16 v[40:43], v[174:177], v[198:201], v[40:43]
	v_mfma_f32_16x16x32_bf16 v[32:35], v[182:185], v[198:201], v[32:35]
	v_mfma_f32_16x16x32_bf16 v[24:27], v[174:177], v[206:209], v[24:27]
	v_mfma_f32_16x16x32_bf16 v[16:19], v[182:185], v[206:209], v[16:19]
	v_mfma_f32_16x16x32_bf16 v[8:11], v[174:177], v[214:217], v[8:11]
	v_mfma_f32_16x16x32_bf16 v[0:3], v[182:185], v[214:217], v[0:3]
	s_setprio 0
	s_barrier
	s_mov_b32 s32, 0
	s_add_i32 s62, s62, 2
	s_add_u32 s36, s36, 0x100
	s_addc_u32 s37, s37, 0
	s_add_u32 s60, s60, 0x100
	s_addc_u32 s61, s61, 0
	s_cmp_gt_u32 s62, 13
	s_cbranch_scc0 .LBB0_1342
	s_and_b64 vcc, exec, s[12:13]
	s_cbranch_vccz .LBB0_1345
	s_barrier
